# attention loop: K/V prefetch addresses kept in six loop-carried pointers (no per-load 64-bit address rebuild); fmaxf canonicalisation triples collapsed; row-sum chains no longer start from 0+x
# speedup vs baseline: 1.1099x; 1.0113x over previous
; DEVI int v_st(int k, int c) { const int kk = (k & ~0xC) | ((k & 4) << 1) | ((k & 8) >> 1); return ((kk >> 3) * 2 + (c >> 5)) * 512 + ((kk & 7) * 32 + (c & 31)) * 2; }
; DEVI int v_rd_base(int lane) { return ((lane & 3) << 3) | (((lane >> 2) & 3) << 6) | (((lane >> 4) & 1) << 5) | (((lane >> 5) & 1) << 8); }
; #define SLOAD(i, k0) do { sr_[i].vs = *reinterpret_cast<const bf16x8*>(Vh + (size_t)(k0) * 64 + tid * 8);      \
;     sr_[i].ks0 = *reinterpret_cast<const bf16x8*>(Kh + (size_t)(k0) * 96 + tid * 8);                          \
;     sr_[i].ks1 = *reinterpret_cast<const bf16x8*>(Kh + (size_t)(k0) * 96 + idx1 * 8); } while (0)
; #define SWRITE(b, i) do { *(bf16x8*)(V_lds + (b) * SHM_V + vst0) = sr_[i].vs;                                  \
;     *(bf16x8*)(K_lds + (b) * SHM_K + kst0) = sr_[i].ks0;                                                      \
;     if (w1) *(bf16x8*)(K_lds + (b) * SHM_K + kst1) = sr_[i].ks1; } while (0)
; #define SWAIT() asm volatile("s_waitcnt vmcnt(3)" ::: "memory")
; DEVI void attn_unit(const u16* __restrict__ Qb, const u16* __restrict__ Kh, const u16* __restrict__ Vh, u16* __restrict__ Yrow0, int seq, char* lds) {
;     ...
;   const u16* Qw = Qb + (size_t)(wid * 32 + r32) * 96 + hi * 8;
; #pragma unroll
;   for (int d0 = 0; d0 < 6; ++d0) qr[d0] = *reinterpret_cast<const bf16x8*>(Qw + d0 * 16);
;   const int vst0 = v_st(tid >> 3, (tid & 7) * 8);
;   const int kst0 = (tid / 12) * KROW + (tid % 12) * 16;
;   const int idx1 = 512 + (tid & 255);
;   const int kst1 = (idx1 / 12) * KROW + (idx1 % 12) * 16;
;   const bool w1 = tid < 256;
;   const int vb0 = (int)(uintptr_t)V_lds + v_rd_base(lane);
;   struct { bf16x8 vs, ks0, ks1; } sr_[2];
;     ...
;   f32x16 pA0, pA1, pB0, pB1; float mnA, mnB, alA, alB; bf16x8 pa0, pa1, pa2, pa3; const int NT = seq / 64;
;   constexpr int SE = 0, SO = 1;
;   SLOAD(SE, 0); asm volatile("s_waitcnt vmcnt(0)" ::: "memory"); SWRITE(0, SE); __syncthreads();
;   qkt(pA0, pA1, K_lds, qr, r32, hi, -m_reg); partialSM(pA0, pA1, m_reg, mnA, alA);
;   SLOAD(SO, 64); if (2 < NT) SLOAD(SE, 128);
;   SWAIT(); SWRITE(1, SO); __syncthreads();
;   const bool lateQ = (wid & 4) != 0;
;   for (int j = 1; j + 1 < NT; j += 2) {
.LBB0_726:
	s_or_b64 exec, exec, s[8:9]
	v_and_b32_e32 v18, 63, v20
	s_and_b64 s[6:7], s[30:31], exec
	v_exp_f32_e32 v171, v0
	v_exp_f32_e32 v173, v1
	s_cselect_b32 s8, 64, 0x100
	v_and_b32_e32 v0, 0x3fffffc0, v20
	s_add_i32 s6, 16, 0x15000
	v_lshlrev_b32_e32 v1, 4, v18
	v_exp_f32_e32 v126, v2
	v_lshl_add_u32 v160, v0, 2, s6
	v_lshlrev_b32_e32 v0, 3, v18
	v_and_b32_e32 v1, 0xc0, v1
	v_lshlrev_b32_e32 v2, 1, v18
	v_and_or_b32 v1, v0, 24, v1
	v_and_b32_e32 v2, 32, v2
	v_and_b32_e32 v0, 0x100, v0
	s_cmp_lg_u32 16, -1
	s_mul_i32 s30, s29, 0xc0
	s_mul_hi_u32 s31, s28, 0xc0
	v_or3_b32 v162, v1, v2, v0
	s_cselect_b32 s6, 16, 0
	s_mul_i32 s7, s60, 0x480
	s_add_i32 s31, s31, s30
	s_mul_i32 s30, s28, 0xc0
	v_add_u32_e32 v168, s6, v162
	s_mul_hi_i32 s6, s60, 0x480
	s_add_u32 s7, s7, s30
	s_addc_u32 s30, s6, s31
	v_readlane_b32 s82, v221, 1
	v_and_b32_e32 v0, 0x100, v20
	v_readlane_b32 s83, v221, 2
	s_add_u32 s6, s82, s7
	v_cmp_ne_u32_e64 s[42:43], 0, v0
	s_addc_u32 s7, s83, s30
	v_lshlrev_b32_sdwa v0, v141, v20 dst_sel:DWORD dst_unused:UNUSED_PAD src0_sel:DWORD src1_sel:BYTE_0
	v_mov_b32_e32 v1, v129
	v_lshl_add_u64 v[132:133], s[6:7], 0, v[16:17]
	v_lshl_add_u64 v[134:135], s[6:7], 0, v[0:1]
	s_mul_i32 s31, s60, 0x300
	s_lshl_b64 s[6:7], s[28:29], 7
	s_mul_hi_i32 s30, s60, 0x300
	s_add_u32 s6, s31, s6
	s_addc_u32 s7, s30, s7
	v_exp_f32_e32 v172, v3
	v_exp_f32_e32 v123, v4
	v_exp_f32_e32 v125, v5
	v_exp_f32_e32 v122, v6
	v_exp_f32_e32 v124, v7
	v_exp_f32_e32 v119, v8
	v_exp_f32_e32 v121, v9
	v_exp_f32_e32 v117, v10
	v_exp_f32_e32 v120, v11
	v_exp_f32_e32 v115, v12
	v_exp_f32_e32 v118, v13
	v_exp_f32_e32 v114, v14
	v_exp_f32_e32 v116, v15
	s_add_u32 s6, s82, s6
	s_addc_u32 s7, s83, s7
	v_mov_b32_e32 v14, v129
	v_mov_b32_e32 v15, v129
	v_and_b32_e32 v159, 0xffffffe0, v21
	v_cmp_gt_u32_e64 s[38:39], 32, v18
	v_lshl_add_u64 v[136:137], s[6:7], 0, v[16:17]
	v_mov_b32_e32 v0, v129
	v_mov_b32_e32 v2, v129
	v_mov_b32_e32 v3, v129
	v_mov_b32_e32 v4, v129
	v_mov_b32_e32 v5, v129
	v_mov_b32_e32 v6, v129
	v_mov_b32_e32 v7, v129
	v_mov_b32_e32 v8, v129
	v_mov_b32_e32 v9, v129
	v_mov_b32_e32 v10, v129
	v_mov_b32_e32 v11, v129
	v_mov_b32_e32 v12, v129
	v_mov_b32_e32 v13, v129
	v_mov_b64_e32 v[30:31], v[14:15]
	s_mov_b32 s9, 2
	v_lshl_add_u32 v161, v158, 2, v160
	v_mov_b32_e32 v113, 0
	s_mov_b32 s28, 0x8000
	v_mov_b64_e32 v[28:29], v[12:13]
	v_mov_b64_e32 v[26:27], v[10:11]
	v_mov_b64_e32 v[24:25], v[8:9]
	v_mov_b64_e32 v[22:23], v[6:7]
	v_mov_b64_e32 v[20:21], v[4:5]
	v_mov_b64_e32 v[18:19], v[2:3]
	v_mov_b64_e32 v[16:17], v[0:1]
	s_waitcnt lgkmcnt(0)
	s_barrier
	v_lshl_add_u64 v[196:197], v[136:137], 0, s[80:81]
	v_add_co_u32_e32 v196, vcc, 0x1c2b6000, v196
	s_nop 1
	v_addc_co_u32_e32 v197, vcc, 0, v197, vcc
	v_lshl_add_u64 v[198:199], v[132:133], 0, s[80:81]
	v_add_co_u32_e32 v198, vcc, 0x156b9000, v198
	s_nop 1
	v_addc_co_u32_e32 v199, vcc, 0, v199, vcc
	v_lshl_add_u64 v[200:201], v[134:135], 0, s[80:81]
	v_add_co_u32_e32 v200, vcc, 0x156bb000, v200
	s_nop 1
	v_addc_co_u32_e32 v201, vcc, 0, v201, vcc
	v_lshl_add_u64 v[202:203], v[136:137], 0, s[80:81]
	v_add_co_u32_e32 v202, vcc, 0x1c2b8000, v202
	s_nop 1
	v_addc_co_u32_e32 v203, vcc, 0, v203, vcc
	v_lshl_add_u64 v[204:205], v[132:133], 0, s[80:81]
	v_add_co_u32_e32 v204, vcc, 0x156bc000, v204
	s_nop 1
	v_addc_co_u32_e32 v205, vcc, 0, v205, vcc
	v_lshl_add_u64 v[206:207], v[134:135], 0, s[80:81]
	v_add_co_u32_e32 v206, vcc, 0x156be000, v206
	s_nop 1
	v_addc_co_u32_e32 v207, vcc, 0, v207, vcc
	s_branch .LBB0_729

; #define SBAR() __builtin_amdgcn_sched_barrier(0)
; #define SLOAD(i, k0) do { sr_[i].vs = *reinterpret_cast<const bf16x8*>(Vh + (size_t)(k0) * 64 + tid * 8);      \
;     sr_[i].ks0 = *reinterpret_cast<const bf16x8*>(Kh + (size_t)(k0) * 96 + tid * 8);                          \
;     sr_[i].ks1 = *reinterpret_cast<const bf16x8*>(Kh + (size_t)(k0) * 96 + idx1 * 8); } while (0)
; #define SWRITE(b, i) do { *(bf16x8*)(V_lds + (b) * SHM_V + vst0) = sr_[i].vs;                                  \
;     *(bf16x8*)(K_lds + (b) * SHM_K + kst0) = sr_[i].ks0;                                                      \
;     if (w1) *(bf16x8*)(K_lds + (b) * SHM_K + kst1) = sr_[i].ks1; } while (0)
; #define SWAIT() asm volatile("s_waitcnt vmcnt(3)" ::: "memory")
; #define RESC(a) do { if (__any((a) < 1.f)) { if (hi == 0) al_l[r32] = (a); asm volatile("s_waitcnt lgkmcnt(0)" ::: "memory"); \
;     _Pragma("unroll") for (int dd = 0; dd < 2; ++dd) _Pragma("unroll") for (int r = 0; r < 16; ++r) o[dd][r] *= al_l[crow(r, hi)]; } } while (0)
; DEVI void attn_unit(const u16* __restrict__ Qb, const u16* __restrict__ Kh, const u16* __restrict__ Vh, u16* __restrict__ Yrow0, int seq, char* lds) {
;     ...
;   for (int j = 1; j + 1 < NT; j += 2) {
;     ...
;       pv_d0(o, vj1, pa0, pa1, pa2, pa3); partialSM(pA0, pA1, m_reg, mnA, alA);
;     } else {
;       SBAR(); finishSM(pB0, pB1, alB, l_reg, pa0, pa1, pa2, pa3);
;       if (j + 3 < NT) SLOAD(SE, (j + 3) * 64); SBAR();
;       pv_d0(o, vj1, pa0, pa1, pa2, pa3); SBAR();
;       qkt(pA0, pA1, Kj1, qr, r32, hi, -m_reg); partialSM(pA0, pA1, m_reg, mnA, alA);
;     }
;     SWAIT(); SWRITE((j + 2) & 3, SO);
;     RESC(alA); __syncthreads();
;   }
.LBB0_728:
	v_exp_f32_e32 v171, v48
	v_exp_f32_e32 v173, v49
	v_exp_f32_e32 v126, v50
	v_exp_f32_e32 v172, v51
	v_exp_f32_e32 v123, v52
	v_exp_f32_e32 v125, v53
	v_exp_f32_e32 v122, v54
	v_exp_f32_e32 v124, v55
	v_exp_f32_e32 v119, v56
	v_exp_f32_e32 v121, v57
	v_exp_f32_e32 v117, v58
	v_exp_f32_e32 v120, v59
	v_exp_f32_e32 v115, v60
	v_exp_f32_e32 v118, v61
	v_exp_f32_e32 v114, v62
	v_exp_f32_e32 v116, v63
	s_add_i32 s9, s9, 2
	s_addk_i32 s28, 0x4000
	s_mov_b64 s[6:7], 0x4000
	v_lshl_add_u64 v[132:133], v[132:133], 0, s[36:37]
	v_lshl_add_u64 v[134:135], v[134:135], 0, s[36:37]
	s_cmp_ge_u32 s9, s8
	v_lshl_add_u64 v[136:137], v[136:137], 0, s[6:7]
	v_lshl_add_u64 v[196:197], v[196:197], 0, s[6:7]
	v_lshl_add_u64 v[198:199], v[198:199], 0, s[36:37]
	v_lshl_add_u64 v[200:201], v[200:201], 0, s[36:37]
	v_lshl_add_u64 v[202:203], v[202:203], 0, s[6:7]
	v_lshl_add_u64 v[204:205], v[204:205], 0, s[36:37]
	v_lshl_add_u64 v[206:207], v[206:207], 0, s[36:37]
	s_waitcnt lgkmcnt(0)
	s_barrier
	s_cbranch_scc1 .LBB0_760
; DEVI void partialSM(f32x16& p0, f32x16& p1, float& m_reg, float& mn, float& alpha) {
;   constexpr float THR2 = THR * 1.4426950408889634f;
;   float pmax = p0[0];
; #pragma unroll
;   for (int r = 1; r < 16; ++r) pmax = fmaxf(pmax, p0[r]);
; #pragma unroll
;   for (int r = 0; r < 16; ++r) pmax = fmaxf(pmax, p1[r]);
;   { auto rr = __builtin_amdgcn_permlane32_swap(__float_as_uint(pmax), __float_as_uint(pmax), false, false);
;     pmax = fmaxf(__uint_as_float(rr[0]), __uint_as_float(rr[1])); }
;   mn = m_reg;
;   if (__builtin_expect(__all(pmax <= THR2), 1)) { alpha = 1.f; }
;   else {
;     const float d = fmaxf(pmax, 0.f);
;     alpha = __builtin_amdgcn_exp2f(-d); m_reg += d;
; #pragma unroll
;     for (int r = 0; r < 16; ++r) p0[r] -= d;
; #pragma unroll
;     for (int r = 0; r < 16; ++r) p1[r] -= d;
;   }
; #pragma unroll
;   for (int r = 0; r < 16; ++r) p0[r] = __builtin_amdgcn_exp2f(p0[r]);
; }
; DEVI void finishSM(f32x16& p0, f32x16& p1, float alpha, float& l_reg, bf16x8& pa0, bf16x8& pa1, bf16x8& pa2, bf16x8& pa3) {
; #pragma unroll
;   for (int r = 0; r < 16; ++r) p1[r] = __builtin_amdgcn_exp2f(p1[r]);
;   float ps = 0;
; #pragma unroll
;   for (int r = 0; r < 16; ++r) ps += p0[r];
; #pragma unroll
;   for (int r = 0; r < 16; ++r) ps += p1[r];
;   { auto rr = __builtin_amdgcn_permlane32_swap(__float_as_uint(ps), __float_as_uint(ps), false, false);
;     ps = __uint_as_float(rr[0]) + __uint_as_float(rr[1]); }
;   l_reg = l_reg * alpha + ps;
;     ...
;   PK4(p0, 0, pa0); PK4(p0, 8, pa1); PK4(p1, 0, pa2); PK4(p1, 8, pa3);
;     ...
; }
; DEVI void qkt(f32x16& p0, f32x16& p1, const char* Ks, const bf16x8* qr, int r32, int hi, float minit) {
; #pragma unroll
;   for (int r = 0; r < 16; ++r) { p0[r] = minit; p1[r] = minit; }
; #pragma unroll
;   for (int d0 = 0; d0 < 6; ++d0) {
;     int cb = d0 * 32 + hi * 16;
;     bf16x8 b0 = *reinterpret_cast<const bf16x8*>(Ks + r32 * KROW + cb);
;     bf16x8 b1 = *reinterpret_cast<const bf16x8*>(Ks + (32 + r32) * KROW + cb);
;     p0 = __builtin_amdgcn_mfma_f32_32x32x16_bf16(b0, qr[d0], p0, 0, 0, 0);
;     p1 = __builtin_amdgcn_mfma_f32_32x32x16_bf16(b1, qr[d0], p1, 0, 0, 0);
;   }
; }
; DEVI int v_st(int k, int c) { const int kk = (k & ~0xC) | ((k & 4) << 1) | ((k & 8) >> 1); return ((kk >> 3) * 2 + (c >> 5)) * 512 + ((kk & 7) * 32 + (c & 31)) * 2; }
.LBB0_729:
	s_add_i32 s6, s9, -1
	s_and_b32 s29, s6, 3
	v_exp_f32_e32 v184, v32
	v_exp_f32_e32 v185, v33
	v_exp_f32_e32 v186, v34
	v_exp_f32_e32 v187, v35
	v_exp_f32_e32 v188, v36
	v_exp_f32_e32 v189, v37
	v_exp_f32_e32 v190, v38
	v_exp_f32_e32 v191, v39
	v_exp_f32_e32 v176, v40
	v_exp_f32_e32 v177, v41
	v_exp_f32_e32 v178, v42
	v_exp_f32_e32 v179, v43
	v_exp_f32_e32 v180, v44
	v_exp_f32_e32 v181, v45
	v_exp_f32_e32 v182, v46
	v_exp_f32_e32 v183, v47
	s_mul_i32 s6, s29, 0x3400
	s_add_i32 s6, s6, 16
	s_and_b32 s7, s28, 0x6000
	v_add_u32_e32 v127, s7, v168
	v_xor_b32_e32 v32, 0x80000000, v167
	v_add3_u32 v174, s6, v166, v128
	v_add_f32_e32 v175, v173, v171
	s_and_saveexec_b64 s[6:7], s[42:43]
	s_xor_b64 s[6:7], exec, s[6:7]
	s_cbranch_execz .LBB0_732
	v_cvt_pk_bf16_f32 v34, v171, v173
	v_cvt_pk_bf16_f32 v35, v126, v172
	v_cvt_pk_bf16_f32 v36, v123, v125
	v_cvt_pk_bf16_f32 v37, v122, v124
	v_cvt_pk_bf16_f32 v38, v119, v121
	v_cvt_pk_bf16_f32 v39, v117, v120
	v_cvt_pk_bf16_f32 v40, v115, v118
	v_cvt_pk_bf16_f32 v41, v114, v116
	v_cvt_pk_bf16_f32 v42, v184, v185
	v_cvt_pk_bf16_f32 v43, v186, v187
	v_cvt_pk_bf16_f32 v44, v188, v189
	v_cvt_pk_bf16_f32 v45, v190, v191
	v_cvt_pk_bf16_f32 v46, v176, v177
	v_cvt_pk_bf16_f32 v47, v178, v179
	v_cvt_pk_bf16_f32 v48, v180, v181
	v_cvt_pk_bf16_f32 v49, v182, v183
	global_load_dwordx4 v[76:79], v[196:197], off
	global_load_dwordx4 v[104:107], v[198:199], off
	v_add_f32_e32 v33, v126, v175
	global_load_dwordx4 v[108:111], v[200:201], off
	v_add_f32_e32 v33, v172, v33
	v_add_f32_e32 v33, v123, v33
	v_add_f32_e32 v33, v125, v33
	v_add_f32_e32 v33, v122, v33
	v_add_f32_e32 v33, v124, v33
	v_add_f32_e32 v33, v119, v33
	v_add_f32_e32 v33, v121, v33
	v_add_f32_e32 v33, v117, v33
	v_add_f32_e32 v33, v120, v33
	v_add_f32_e32 v33, v115, v33
	v_add_f32_e32 v33, v118, v33
	v_add_f32_e32 v33, v114, v33
	v_add_f32_e32 v33, v116, v33
	v_add_f32_e32 v33, v184, v33
	v_add_f32_e32 v33, v185, v33
	v_add_f32_e32 v33, v186, v33
	v_add_f32_e32 v33, v187, v33
	v_add_f32_e32 v33, v188, v33
	v_add_f32_e32 v33, v189, v33
	v_add_f32_e32 v33, v190, v33
	v_add_f32_e32 v33, v191, v33
	v_add_f32_e32 v33, v176, v33
	v_add_f32_e32 v33, v177, v33
	v_add_f32_e32 v33, v178, v33
	v_add_f32_e32 v33, v179, v33
	v_add_f32_e32 v33, v180, v33
	v_add_f32_e32 v33, v181, v33
	v_add_f32_e32 v33, v182, v33
	v_add_f32_e32 v170, v183, v33
	v_mov_b32_e32 v175, v170
	s_nop 1
	v_permlane32_swap_b32_e32 v170, v175
	v_permlane32_swap_b32_e32 v34, v36
	v_permlane32_swap_b32_e32 v35, v37
	v_permlane32_swap_b32_e32 v38, v40
	v_permlane32_swap_b32_e32 v39, v41
	v_permlane32_swap_b32_e32 v42, v44
	v_permlane32_swap_b32_e32 v43, v45
	v_permlane32_swap_b32_e32 v46, v48
	v_permlane32_swap_b32_e32 v47, v49
	ds_read_b64_tr_b16 v[50:51], v127 offset:0
	ds_read_b64_tr_b16 v[52:53], v127 offset:0x400
	ds_read_b64_tr_b16 v[54:55], v127 offset:0x800
	ds_read_b64_tr_b16 v[56:57], v127 offset:0xc00
	ds_read_b64_tr_b16 v[58:59], v127 offset:0x1000
	ds_read_b64_tr_b16 v[60:61], v127 offset:0x1400
	ds_read_b64_tr_b16 v[114:115], v127 offset:0x1800
	ds_read_b64_tr_b16 v[116:117], v127 offset:0x1c00
	s_waitcnt lgkmcnt(0)
	s_nop 0
	v_mfma_f32_32x32x16_bf16 v[0:15], v[34:37], v[50:53], v[0:15]
	ds_read_b64_tr_b16 v[50:51], v127 offset:0x200
	ds_read_b64_tr_b16 v[52:53], v127 offset:0x600
	v_mfma_f32_32x32x16_bf16 v[0:15], v[38:41], v[54:57], v[0:15]
	ds_read_b64_tr_b16 v[54:55], v127 offset:0xa00
	ds_read_b64_tr_b16 v[56:57], v127 offset:0xe00
	v_mfma_f32_32x32x16_bf16 v[0:15], v[42:45], v[58:61], v[0:15]
	ds_read_b64_tr_b16 v[58:59], v127 offset:0x1200
	ds_read_b64_tr_b16 v[60:61], v127 offset:0x1600
	v_mfma_f32_32x32x16_bf16 v[0:15], v[46:49], v[114:117], v[0:15]
	ds_read_b64_tr_b16 v[114:115], v127 offset:0x1a00
	ds_read_b64_tr_b16 v[116:117], v127 offset:0x1e00
	s_waitcnt lgkmcnt(0)
	v_mfma_f32_32x32x16_bf16 v[16:31], v[34:37], v[50:53], v[16:31]
	v_mfma_f32_32x32x16_bf16 v[16:31], v[38:41], v[54:57], v[16:31]
	v_mfma_f32_32x32x16_bf16 v[16:31], v[42:45], v[58:61], v[16:31]
	v_mfma_f32_32x32x16_bf16 v[16:31], v[46:49], v[114:117], v[16:31]
	ds_read_b128 v[222:225], v174 offset:32768
	ds_read_b128 v[226:229], v174 offset:39424
	ds_read_b128 v[230:233], v174 offset:32800
	ds_read_b128 v[234:237], v174 offset:39456
	ds_read_b128 v[238:241], v174 offset:32832
	ds_read_b128 v[242:245], v174 offset:39488
	ds_read_b128 v[246:249], v174 offset:32864
	ds_read_b128 v[250:253], v174 offset:39520
	v_mov_b32_e32 v33, v32
	v_mov_b32_e32 v34, v32
	v_mov_b32_e32 v35, v32
	v_mov_b32_e32 v36, v32
	v_mov_b32_e32 v37, v32
	v_mov_b32_e32 v38, v32
	v_mov_b32_e32 v39, v32
	v_mov_b32_e32 v40, v32
	v_mov_b32_e32 v41, v32
	v_mov_b32_e32 v42, v32
	v_mov_b32_e32 v43, v32
	v_mov_b32_e32 v44, v32
	v_mov_b32_e32 v45, v32
	v_mov_b32_e32 v46, v32
	v_mov_b32_e32 v47, v32
	s_mov_b32 s4, 0x4138aa3b
	v_mov_b32_e32 v169, 1.0
	s_waitcnt lgkmcnt(7)
	v_mfma_f32_32x32x16_bf16 v[48:63], v[222:225], v[100:103], v[32:47]
	s_waitcnt lgkmcnt(6)
	v_mfma_f32_32x32x16_bf16 v[32:47], v[226:229], v[100:103], v[32:47]
	ds_read_b128 v[222:225], v174 offset:32896
	ds_read_b128 v[226:229], v174 offset:32928
	s_waitcnt lgkmcnt(7)
	v_mfma_f32_32x32x16_bf16 v[48:63], v[230:233], v[96:99], v[48:63]
	s_waitcnt lgkmcnt(6)
	v_mfma_f32_32x32x16_bf16 v[32:47], v[234:237], v[96:99], v[32:47]
	ds_read_b128 v[230:233], v174 offset:39552
	ds_read_b128 v[234:237], v174 offset:39584
	s_waitcnt lgkmcnt(7)
	v_mfma_f32_32x32x16_bf16 v[48:63], v[238:241], v[92:95], v[48:63]
	s_waitcnt lgkmcnt(6)
	v_mfma_f32_32x32x16_bf16 v[32:47], v[242:245], v[92:95], v[32:47]
	s_waitcnt lgkmcnt(5)
	v_mfma_f32_32x32x16_bf16 v[48:63], v[246:249], v[88:91], v[48:63]
	s_waitcnt lgkmcnt(4)
	v_mfma_f32_32x32x16_bf16 v[32:47], v[250:253], v[88:91], v[32:47]
	s_waitcnt lgkmcnt(3)
	v_mfma_f32_32x32x16_bf16 v[48:63], v[222:225], v[84:87], v[48:63]
	s_waitcnt lgkmcnt(2)
	v_mfma_f32_32x32x16_bf16 v[48:63], v[226:229], v[80:83], v[48:63]
	s_waitcnt lgkmcnt(1)
	v_mfma_f32_32x32x16_bf16 v[32:47], v[230:233], v[84:87], v[32:47]
	s_nop 7
	v_max_f32_e32 v122, v48, v49
	v_max3_f32 v114, v122, v50, v51
	v_max3_f32 v114, v114, v52, v53
	v_max3_f32 v114, v114, v54, v55
	v_max3_f32 v114, v114, v56, v57
	s_waitcnt lgkmcnt(0)
	v_mfma_f32_32x32x16_bf16 v[32:47], v[234:237], v[80:83], v[32:47]
	v_max3_f32 v114, v114, v58, v59
	v_max3_f32 v114, v114, v60, v61
	v_max3_f32 v114, v114, v62, v63
	s_nop 8
	v_max3_f32 v114, v114, v32, v33
	v_max3_f32 v114, v114, v34, v35
	v_max3_f32 v114, v114, v36, v37
	v_max3_f32 v114, v114, v38, v39
	v_max3_f32 v114, v114, v40, v41
	v_max3_f32 v114, v114, v42, v43
	v_max3_f32 v114, v114, v44, v45
	v_max3_f32 v114, v114, v46, v47
	v_mov_b32_e32 v115, v114
	s_nop 1
	v_permlane32_swap_b32_e32 v114, v115
	v_max_f32_e32 v114, v114, v115
	v_cmp_ge_f32_e32 vcc, s4, v114
	s_cmp_eq_u64 vcc, exec
	s_cbranch_scc0 .LBB0_756

; DEVI void partialSM(f32x16& p0, f32x16& p1, float& m_reg, float& mn, float& alpha) {
;   constexpr float THR2 = THR * 1.4426950408889634f;
;   float pmax = p0[0];
; #pragma unroll
;   for (int r = 1; r < 16; ++r) pmax = fmaxf(pmax, p0[r]);
; #pragma unroll
;   for (int r = 0; r < 16; ++r) pmax = fmaxf(pmax, p1[r]);
;   { auto rr = __builtin_amdgcn_permlane32_swap(__float_as_uint(pmax), __float_as_uint(pmax), false, false);
;     pmax = fmaxf(__uint_as_float(rr[0]), __uint_as_float(rr[1])); }
;   mn = m_reg;
;   if (__builtin_expect(__all(pmax <= THR2), 1)) { alpha = 1.f; }
;   else {
;     const float d = fmaxf(pmax, 0.f);
;     alpha = __builtin_amdgcn_exp2f(-d); m_reg += d;
; #pragma unroll
;     for (int r = 0; r < 16; ++r) p0[r] -= d;
; #pragma unroll
;     for (int r = 0; r < 16; ++r) p1[r] -= d;
;   }
; #pragma unroll
;   for (int r = 0; r < 16; ++r) p0[r] = __builtin_amdgcn_exp2f(p0[r]);
; }
; DEVI void finishSM(f32x16& p0, f32x16& p1, float alpha, float& l_reg, bf16x8& pa0, bf16x8& pa1, bf16x8& pa2, bf16x8& pa3) {
; #pragma unroll
;   for (int r = 0; r < 16; ++r) p1[r] = __builtin_amdgcn_exp2f(p1[r]);
;   float ps = 0;
; #pragma unroll
;   for (int r = 0; r < 16; ++r) ps += p0[r];
; #pragma unroll
;   for (int r = 0; r < 16; ++r) ps += p1[r];
;   { auto rr = __builtin_amdgcn_permlane32_swap(__float_as_uint(ps), __float_as_uint(ps), false, false);
;     ps = __uint_as_float(rr[0]) + __uint_as_float(rr[1]); }
;   l_reg = l_reg * alpha + ps;
;     ...
;   PK4(p0, 0, pa0); PK4(p0, 8, pa1); PK4(p1, 0, pa2); PK4(p1, 8, pa3);
;     ...
; }
; DEVI void qkt(f32x16& p0, f32x16& p1, const char* Ks, const bf16x8* qr, int r32, int hi, float minit) {
; #pragma unroll
;   for (int r = 0; r < 16; ++r) { p0[r] = minit; p1[r] = minit; }
; #pragma unroll
;   for (int d0 = 0; d0 < 6; ++d0) {
;     int cb = d0 * 32 + hi * 16;
;     bf16x8 b0 = *reinterpret_cast<const bf16x8*>(Ks + r32 * KROW + cb);
;     bf16x8 b1 = *reinterpret_cast<const bf16x8*>(Ks + (32 + r32) * KROW + cb);
;     p0 = __builtin_amdgcn_mfma_f32_32x32x16_bf16(b0, qr[d0], p0, 0, 0, 0);
;     p1 = __builtin_amdgcn_mfma_f32_32x32x16_bf16(b1, qr[d0], p1, 0, 0, 0);
;   }
; }
; DEVI void attn_unit(const u16* __restrict__ Qb, const u16* __restrict__ Kh, const u16* __restrict__ Vh, u16* __restrict__ Yrow0, int seq, char* lds) {
;     ...
;       SBAR(); qkt(pB0, pB1, Kj, qr, r32, hi, -m_reg);
.LBB0_732:
	s_andn2_saveexec_b64 s[6:7], s[6:7]
	s_cbranch_execz .LBB0_735
	ds_read_b128 v[222:225], v174 offset:32768
	ds_read_b128 v[226:229], v174 offset:39424
	ds_read_b128 v[230:233], v174 offset:32800
	ds_read_b128 v[234:237], v174 offset:39456
	ds_read_b128 v[238:241], v174 offset:32832
	ds_read_b128 v[242:245], v174 offset:39488
	ds_read_b128 v[246:249], v174 offset:32864
	ds_read_b128 v[250:253], v174 offset:39520
	v_mov_b32_e32 v33, v32
	v_mov_b32_e32 v34, v32
	v_mov_b32_e32 v35, v32
	v_mov_b32_e32 v36, v32
	v_mov_b32_e32 v37, v32
	v_mov_b32_e32 v38, v32
	v_mov_b32_e32 v39, v32
	v_mov_b32_e32 v40, v32
	v_mov_b32_e32 v41, v32
	v_mov_b32_e32 v42, v32
	v_mov_b32_e32 v43, v32
	v_mov_b32_e32 v44, v32
	v_mov_b32_e32 v45, v32
	v_mov_b32_e32 v46, v32
	v_mov_b32_e32 v47, v32
	s_waitcnt lgkmcnt(7)
	s_nop 0
	v_mfma_f32_32x32x16_bf16 v[48:63], v[222:225], v[100:103], v[32:47]
	s_waitcnt lgkmcnt(6)
	v_mfma_f32_32x32x16_bf16 v[32:47], v[226:229], v[100:103], v[32:47]
	ds_read_b128 v[222:225], v174 offset:32896
	ds_read_b128 v[226:229], v174 offset:39552
	s_waitcnt lgkmcnt(7)
	v_mfma_f32_32x32x16_bf16 v[48:63], v[230:233], v[96:99], v[48:63]
	s_waitcnt lgkmcnt(6)
	v_mfma_f32_32x32x16_bf16 v[32:47], v[234:237], v[96:99], v[32:47]
	ds_read_b128 v[230:233], v174 offset:32928
	ds_read_b128 v[234:237], v174 offset:39584
	s_waitcnt lgkmcnt(7)
	v_mfma_f32_32x32x16_bf16 v[48:63], v[238:241], v[92:95], v[48:63]
	s_waitcnt lgkmcnt(6)
	v_mfma_f32_32x32x16_bf16 v[32:47], v[242:245], v[92:95], v[32:47]
	s_waitcnt lgkmcnt(5)
	v_mfma_f32_32x32x16_bf16 v[48:63], v[246:249], v[88:91], v[48:63]
	s_waitcnt lgkmcnt(4)
	v_mfma_f32_32x32x16_bf16 v[32:47], v[250:253], v[88:91], v[32:47]
	s_waitcnt lgkmcnt(3)
	v_mfma_f32_32x32x16_bf16 v[48:63], v[222:225], v[84:87], v[48:63]
	s_waitcnt lgkmcnt(2)
	v_mfma_f32_32x32x16_bf16 v[32:47], v[226:229], v[84:87], v[32:47]
	v_cvt_pk_bf16_f32 v192, v171, v173
	v_cvt_pk_bf16_f32 v193, v126, v172
	v_cvt_pk_bf16_f32 v194, v123, v125
	v_cvt_pk_bf16_f32 v195, v122, v124
	s_nop 0
	v_permlane32_swap_b32_e32 v192, v194
	s_waitcnt lgkmcnt(1)
	v_mfma_f32_32x32x16_bf16 v[48:63], v[230:233], v[80:83], v[48:63]
	v_add_f32_e32 v76, v126, v175
	v_add_f32_e32 v76, v172, v76
	v_add_f32_e32 v76, v123, v76
	v_add_f32_e32 v76, v125, v76
	v_add_f32_e32 v76, v122, v76
	v_add_f32_e32 v76, v124, v76
	v_add_f32_e32 v76, v119, v76
	v_add_f32_e32 v76, v121, v76
	v_add_f32_e32 v76, v117, v76
	v_add_f32_e32 v76, v120, v76
	v_add_f32_e32 v76, v115, v76
	v_add_f32_e32 v76, v118, v76
	v_add_f32_e32 v76, v114, v76
	v_add_f32_e32 v76, v116, v76
	v_add_f32_e32 v76, v184, v76
	v_add_f32_e32 v76, v185, v76
	v_add_f32_e32 v76, v186, v76
	v_add_f32_e32 v76, v187, v76
	v_add_f32_e32 v76, v188, v76
	v_add_f32_e32 v76, v189, v76
	v_add_f32_e32 v76, v190, v76
	v_add_f32_e32 v76, v191, v76
	v_add_f32_e32 v76, v176, v76
	v_add_f32_e32 v76, v177, v76
	s_waitcnt lgkmcnt(0)
	v_mfma_f32_32x32x16_bf16 v[32:47], v[234:237], v[80:83], v[32:47]
	v_add_f32_e32 v76, v178, v76
	v_add_f32_e32 v76, v179, v76
	v_add_f32_e32 v76, v180, v76
	v_add_f32_e32 v76, v181, v76
	v_add_f32_e32 v76, v182, v76
	v_add_f32_e32 v170, v183, v76
	v_mov_b32_e32 v174, v170
	v_cvt_pk_bf16_f32 v122, v119, v121
	v_cvt_pk_bf16_f32 v123, v117, v120
	v_cvt_pk_bf16_f32 v124, v115, v118
	v_cvt_pk_bf16_f32 v125, v114, v116
	v_cvt_pk_bf16_f32 v114, v184, v185
	v_cvt_pk_bf16_f32 v115, v186, v187
	v_cvt_pk_bf16_f32 v116, v188, v189
	s_nop 1
	v_permlane32_swap_b32_e32 v170, v174
	v_cvt_pk_bf16_f32 v117, v190, v191
	v_permlane32_swap_b32_e32 v114, v116
	v_cvt_pk_bf16_f32 v118, v176, v177
	v_cvt_pk_bf16_f32 v119, v178, v179
	v_cvt_pk_bf16_f32 v120, v180, v181
	v_cvt_pk_bf16_f32 v121, v182, v183
	v_permlane32_swap_b32_e32 v193, v195
	v_permlane32_swap_b32_e32 v122, v124
	v_permlane32_swap_b32_e32 v123, v125
	v_permlane32_swap_b32_e32 v115, v117
	v_permlane32_swap_b32_e32 v118, v120
	v_permlane32_swap_b32_e32 v119, v121
	global_load_dwordx4 v[76:79], v[196:197], off
	global_load_dwordx4 v[104:107], v[198:199], off
	global_load_dwordx4 v[108:111], v[200:201], off
	ds_read_b64_tr_b16 v[176:177], v127 offset:0
	ds_read_b64_tr_b16 v[178:179], v127 offset:0x400
	ds_read_b64_tr_b16 v[180:181], v127 offset:0x800
	ds_read_b64_tr_b16 v[182:183], v127 offset:0xc00
	ds_read_b64_tr_b16 v[184:185], v127 offset:0x1000
	ds_read_b64_tr_b16 v[186:187], v127 offset:0x1400
	ds_read_b64_tr_b16 v[188:189], v127 offset:0x1800
	ds_read_b64_tr_b16 v[190:191], v127 offset:0x1c00
	s_waitcnt lgkmcnt(0)
	s_nop 0
	v_mfma_f32_32x32x16_bf16 v[0:15], v[192:195], v[176:179], v[0:15]
	ds_read_b64_tr_b16 v[176:177], v127 offset:0x200
	ds_read_b64_tr_b16 v[178:179], v127 offset:0x600
	v_mfma_f32_32x32x16_bf16 v[0:15], v[122:125], v[180:183], v[0:15]
	ds_read_b64_tr_b16 v[180:181], v127 offset:0xa00
	ds_read_b64_tr_b16 v[182:183], v127 offset:0xe00
	v_mfma_f32_32x32x16_bf16 v[0:15], v[114:117], v[184:187], v[0:15]
	ds_read_b64_tr_b16 v[184:185], v127 offset:0x1200
	ds_read_b64_tr_b16 v[186:187], v127 offset:0x1600
	v_mfma_f32_32x32x16_bf16 v[0:15], v[118:121], v[188:191], v[0:15]
	ds_read_b64_tr_b16 v[188:189], v127 offset:0x1a00
	ds_read_b64_tr_b16 v[190:191], v127 offset:0x1e00
	s_waitcnt lgkmcnt(0)
	v_mfma_f32_32x32x16_bf16 v[16:31], v[192:195], v[176:179], v[16:31]
	s_mov_b32 s4, 0x4138aa3b
	v_mov_b32_e32 v169, 1.0
	v_mfma_f32_32x32x16_bf16 v[16:31], v[122:125], v[180:183], v[16:31]
	v_mfma_f32_32x32x16_bf16 v[16:31], v[114:117], v[184:187], v[16:31]
	v_max_f32_e32 v114, v48, v49
	v_max3_f32 v114, v114, v50, v51
	v_max3_f32 v114, v114, v52, v53
	v_max3_f32 v114, v114, v54, v55
	v_max3_f32 v114, v114, v56, v57
	v_max3_f32 v114, v114, v58, v59
	v_max3_f32 v114, v114, v60, v61
	v_max3_f32 v114, v114, v62, v63
	v_max3_f32 v114, v114, v32, v33
	v_max3_f32 v114, v114, v34, v35
	v_max3_f32 v114, v114, v36, v37
	v_max3_f32 v114, v114, v38, v39
	v_max3_f32 v114, v114, v40, v41
	v_max3_f32 v114, v114, v42, v43
	v_mfma_f32_32x32x16_bf16 v[16:31], v[118:121], v[188:191], v[16:31]
	v_max3_f32 v114, v114, v44, v45
	v_max3_f32 v114, v114, v46, v47
	v_mov_b32_e32 v115, v114
	s_nop 1
	v_permlane32_swap_b32_e32 v114, v115
	v_max_f32_e32 v114, v114, v115
	v_cmp_ge_f32_e32 vcc, s4, v114
	s_cmp_eq_u64 vcc, exec
	s_cbranch_scc0 .LBB0_757

; #define SBAR() __builtin_amdgcn_sched_barrier(0)
; DEVI void partialSM(f32x16& p0, f32x16& p1, float& m_reg, float& mn, float& alpha) {
;   constexpr float THR2 = THR * 1.4426950408889634f;
;   float pmax = p0[0];
; #pragma unroll
;   for (int r = 1; r < 16; ++r) pmax = fmaxf(pmax, p0[r]);
; #pragma unroll
;   for (int r = 0; r < 16; ++r) pmax = fmaxf(pmax, p1[r]);
;   { auto rr = __builtin_amdgcn_permlane32_swap(__float_as_uint(pmax), __float_as_uint(pmax), false, false);
;     pmax = fmaxf(__uint_as_float(rr[0]), __uint_as_float(rr[1])); }
;   mn = m_reg;
;   if (__builtin_expect(__all(pmax <= THR2), 1)) { alpha = 1.f; }
;   else {
;     const float d = fmaxf(pmax, 0.f);
;     alpha = __builtin_amdgcn_exp2f(-d); m_reg += d;
; #pragma unroll
;     for (int r = 0; r < 16; ++r) p0[r] -= d;
; #pragma unroll
;     for (int r = 0; r < 16; ++r) p1[r] -= d;
;   }
; #pragma unroll
;   for (int r = 0; r < 16; ++r) p0[r] = __builtin_amdgcn_exp2f(p0[r]);
; }
; DEVI void finishSM(f32x16& p0, f32x16& p1, float alpha, float& l_reg, bf16x8& pa0, bf16x8& pa1, bf16x8& pa2, bf16x8& pa3) {
; #pragma unroll
;   for (int r = 0; r < 16; ++r) p1[r] = __builtin_amdgcn_exp2f(p1[r]);
;   float ps = 0;
; #pragma unroll
;   for (int r = 0; r < 16; ++r) ps += p0[r];
; #pragma unroll
;   for (int r = 0; r < 16; ++r) ps += p1[r];
;   { auto rr = __builtin_amdgcn_permlane32_swap(__float_as_uint(ps), __float_as_uint(ps), false, false);
;     ps = __uint_as_float(rr[0]) + __uint_as_float(rr[1]); }
;   l_reg = l_reg * alpha + ps;
;     ...
;   PK4(p0, 0, pa0); PK4(p0, 8, pa1); PK4(p1, 0, pa2); PK4(p1, 8, pa3);
; DEVI void attn_unit(const u16* __restrict__ Qb, const u16* __restrict__ Kh, const u16* __restrict__ Vh, u16* __restrict__ Yrow0, int seq, char* lds) {
;     ...
;       finishSM(pB0, pB1, alB, l_reg, pa0, pa1, pa2, pa3); SBAR();
;       if (j + 3 < NT) SLOAD(SE, (j + 3) * 64); SBAR();
;       pv_d0(o, vj1, pa0, pa1, pa2, pa3); partialSM(pA0, pA1, m_reg, mnA, alA);
;     } else {
;       SBAR(); finishSM(pB0, pB1, alB, l_reg, pa0, pa1, pa2, pa3);
;       if (j + 3 < NT) SLOAD(SE, (j + 3) * 64); SBAR();
.LBB0_741:
	v_exp_f32_e32 v187, v48
	v_exp_f32_e32 v189, v49
	v_exp_f32_e32 v185, v50
	v_exp_f32_e32 v188, v51
	v_exp_f32_e32 v114, v52
	v_exp_f32_e32 v186, v53
	v_exp_f32_e32 v115, v54
	v_exp_f32_e32 v184, v55
	v_exp_f32_e32 v116, v56
	v_exp_f32_e32 v183, v57
	v_exp_f32_e32 v117, v58
	v_exp_f32_e32 v182, v59
	v_exp_f32_e32 v118, v60
	v_exp_f32_e32 v181, v61
	v_exp_f32_e32 v119, v62
	v_exp_f32_e32 v180, v63
	v_exp_f32_e32 v120, v32
	v_exp_f32_e32 v121, v33
	v_exp_f32_e32 v122, v34
	v_exp_f32_e32 v123, v35
	v_exp_f32_e32 v176, v36
	v_exp_f32_e32 v177, v37
	v_exp_f32_e32 v178, v38
	v_exp_f32_e32 v179, v39
	v_exp_f32_e32 v124, v40
	v_exp_f32_e32 v125, v41
	v_exp_f32_e32 v126, v42
	v_exp_f32_e32 v127, v43
	v_exp_f32_e32 v172, v44
	v_exp_f32_e32 v173, v45
	v_exp_f32_e32 v174, v46
	v_exp_f32_e32 v175, v47
	v_lshl_add_u32 v171, s29, 13, v168
	v_add_f32_e32 v190, v189, v187
	s_waitcnt lgkmcnt(0)
	s_barrier
	s_and_saveexec_b64 s[6:7], s[42:43]
	s_xor_b64 s[6:7], exec, s[6:7]
	s_cbranch_execz .LBB0_746
	v_add_f32_e32 v32, v185, v190
	v_add_f32_e32 v32, v188, v32
	v_add_f32_e32 v32, v114, v32
	v_add_f32_e32 v32, v186, v32
	v_add_f32_e32 v32, v115, v32
	v_add_f32_e32 v32, v184, v32
	v_add_f32_e32 v32, v116, v32
	v_add_f32_e32 v32, v183, v32
	v_add_f32_e32 v32, v117, v32
	v_add_f32_e32 v32, v182, v32
	v_add_f32_e32 v32, v118, v32
	v_add_f32_e32 v32, v181, v32
	v_add_f32_e32 v32, v119, v32
	v_add_f32_e32 v32, v180, v32
	v_add_f32_e32 v32, v32, v120
	v_add_f32_e32 v32, v121, v32
	v_add_f32_e32 v32, v122, v32
	v_add_f32_e32 v32, v123, v32
	v_add_f32_e32 v32, v176, v32
	v_add_f32_e32 v32, v177, v32
	v_add_f32_e32 v32, v178, v32
	v_add_f32_e32 v32, v179, v32
	v_add_f32_e32 v32, v124, v32
	v_add_f32_e32 v32, v125, v32
	v_add_f32_e32 v32, v126, v32
	v_add_f32_e32 v32, v127, v32
	v_add_f32_e32 v32, v172, v32
	v_add_f32_e32 v32, v173, v32
	v_add_f32_e32 v32, v174, v32
	v_add_f32_e32 v113, v175, v32
	v_mov_b32_e32 v190, v113
	v_cvt_pk_bf16_f32 v32, v187, v189
	v_cvt_pk_bf16_f32 v33, v185, v188
	v_cvt_pk_bf16_f32 v34, v114, v186
	v_cvt_pk_bf16_f32 v35, v115, v184
	v_cvt_pk_bf16_f32 v36, v116, v183
	v_cvt_pk_bf16_f32 v37, v117, v182
	v_cvt_pk_bf16_f32 v38, v118, v181
	v_cvt_pk_bf16_f32 v39, v119, v180
	v_cvt_pk_bf16_f32 v40, v120, v121
	v_cvt_pk_bf16_f32 v41, v122, v123
	v_cvt_pk_bf16_f32 v42, v176, v177
	v_cvt_pk_bf16_f32 v43, v178, v179
	v_cvt_pk_bf16_f32 v44, v124, v125
	v_cvt_pk_bf16_f32 v45, v126, v127
	v_cvt_pk_bf16_f32 v46, v172, v173
	v_cvt_pk_bf16_f32 v47, v174, v175
	s_add_i32 s29, s9, 2
	s_nop 0
	v_permlane32_swap_b32_e32 v113, v190
	v_permlane32_swap_b32_e32 v32, v34
	v_permlane32_swap_b32_e32 v33, v35
	v_permlane32_swap_b32_e32 v36, v38
	v_permlane32_swap_b32_e32 v37, v39
	v_permlane32_swap_b32_e32 v40, v42
	v_permlane32_swap_b32_e32 v41, v43
	v_permlane32_swap_b32_e32 v44, v46
	s_cmp_ge_u32 s29, s8
	v_permlane32_swap_b32_e32 v45, v47
	s_cbranch_scc1 .LBB0_744
	global_load_dwordx4 v[64:67], v[202:203], off
	global_load_dwordx4 v[68:71], v[204:205], off
	global_load_dwordx4 v[72:75], v[206:207], off
; #define SBAR() __builtin_amdgcn_sched_barrier(0)
; DEVI void partialSM(f32x16& p0, f32x16& p1, float& m_reg, float& mn, float& alpha) {
;   constexpr float THR2 = THR * 1.4426950408889634f;
;   float pmax = p0[0];
; #pragma unroll
;   for (int r = 1; r < 16; ++r) pmax = fmaxf(pmax, p0[r]);
; #pragma unroll
;   for (int r = 0; r < 16; ++r) pmax = fmaxf(pmax, p1[r]);
;   { auto rr = __builtin_amdgcn_permlane32_swap(__float_as_uint(pmax), __float_as_uint(pmax), false, false);
; DEVI void qkt(f32x16& p0, f32x16& p1, const char* Ks, const bf16x8* qr, int r32, int hi, float minit) {
; #pragma unroll
;   for (int r = 0; r < 16; ++r) { p0[r] = minit; p1[r] = minit; }
; #pragma unroll
;   for (int d0 = 0; d0 < 6; ++d0) {
;     int cb = d0 * 32 + hi * 16;
;     bf16x8 b0 = *reinterpret_cast<const bf16x8*>(Ks + r32 * KROW + cb);
;     bf16x8 b1 = *reinterpret_cast<const bf16x8*>(Ks + (32 + r32) * KROW + cb);
;     p0 = __builtin_amdgcn_mfma_f32_32x32x16_bf16(b0, qr[d0], p0, 0, 0, 0);
;     p1 = __builtin_amdgcn_mfma_f32_32x32x16_bf16(b1, qr[d0], p1, 0, 0, 0);
;   }
; }
; DEVI int v_st(int k, int c) { const int kk = (k & ~0xC) | ((k & 4) << 1) | ((k & 8) >> 1); return ((kk >> 3) * 2 + (c >> 5)) * 512 + ((kk & 7) * 32 + (c & 31)) * 2; }
; DEVI int v_rd_base(int lane) { return ((lane & 3) << 3) | (((lane >> 2) & 3) << 6) | (((lane >> 4) & 1) << 5) | (((lane >> 5) & 1) << 8); }
; template <int OFF> DEVI s16x4 tr_read(int vb) {
;   s16x4 r; asm volatile("ds_read_b64_tr_b16 %0, %1 offset:%2" : "=&v"(r) : "v"(vb), "i"(OFF) : "memory"); return r;
; }
; template <int D0> DEVI void pv_one(f32x16& od, int vb, bf16x8 pa0, bf16x8 pa1, bf16x8 pa2, bf16x8 pa3) {
;   const s16x4 l0 = tr_read<v_rd_off(D0, 0, 0)>(vb), h0 = tr_read<v_rd_off(D0, 0, 1)>(vb), l1 = tr_read<v_rd_off(D0, 1, 0)>(vb), h1 = tr_read<v_rd_off(D0, 1, 1)>(vb);
;   const s16x4 l2 = tr_read<v_rd_off(D0, 2, 0)>(vb), h2 = tr_read<v_rd_off(D0, 2, 1)>(vb), l3 = tr_read<v_rd_off(D0, 3, 0)>(vb), h3 = tr_read<v_rd_off(D0, 3, 1)>(vb);
;   asm volatile("s_waitcnt lgkmcnt(0)" ::: "memory"); SBAR();
;     ...
;   od = __builtin_amdgcn_mfma_f32_32x32x16_bf16(pa0, PK(l0, h0), od, 0, 0, 0);
;   od = __builtin_amdgcn_mfma_f32_32x32x16_bf16(pa1, PK(l1, h1), od, 0, 0, 0);
;   od = __builtin_amdgcn_mfma_f32_32x32x16_bf16(pa2, PK(l2, h2), od, 0, 0, 0);
;   od = __builtin_amdgcn_mfma_f32_32x32x16_bf16(pa3, PK(l3, h3), od, 0, 0, 0);
;     ...
; }
.LBB0_744:
	ds_read_b64_tr_b16 v[48:49], v171 offset:0
	ds_read_b64_tr_b16 v[50:51], v171 offset:0x400
	ds_read_b64_tr_b16 v[52:53], v171 offset:0x800
	ds_read_b64_tr_b16 v[54:55], v171 offset:0xc00
	ds_read_b64_tr_b16 v[56:57], v171 offset:0x1000
	ds_read_b64_tr_b16 v[58:59], v171 offset:0x1400
	ds_read_b64_tr_b16 v[60:61], v171 offset:0x1800
	ds_read_b64_tr_b16 v[62:63], v171 offset:0x1c00
	s_waitcnt lgkmcnt(0)
	s_nop 0
	v_mfma_f32_32x32x16_bf16 v[0:15], v[32:35], v[48:51], v[0:15]
	ds_read_b64_tr_b16 v[48:49], v171 offset:0x200
	ds_read_b64_tr_b16 v[50:51], v171 offset:0x600
	v_mfma_f32_32x32x16_bf16 v[0:15], v[36:39], v[52:55], v[0:15]
	ds_read_b64_tr_b16 v[52:53], v171 offset:0xa00
	ds_read_b64_tr_b16 v[54:55], v171 offset:0xe00
	v_mfma_f32_32x32x16_bf16 v[0:15], v[40:43], v[56:59], v[0:15]
	ds_read_b64_tr_b16 v[56:57], v171 offset:0x1200
	ds_read_b64_tr_b16 v[58:59], v171 offset:0x1600
	v_mfma_f32_32x32x16_bf16 v[0:15], v[44:47], v[60:63], v[0:15]
	ds_read_b64_tr_b16 v[60:61], v171 offset:0x1a00
	ds_read_b64_tr_b16 v[62:63], v171 offset:0x1e00
	s_waitcnt lgkmcnt(0)
	v_mfma_f32_32x32x16_bf16 v[16:31], v[32:35], v[48:51], v[16:31]
	v_mfma_f32_32x32x16_bf16 v[16:31], v[36:39], v[52:55], v[16:31]
	v_mfma_f32_32x32x16_bf16 v[16:31], v[40:43], v[56:59], v[16:31]
	v_mfma_f32_32x32x16_bf16 v[16:31], v[44:47], v[60:63], v[16:31]
	v_add3_u32 v112, s30, v166, v128
	ds_read_b128 v[222:225], v112 offset:32768
	ds_read_b128 v[226:229], v112 offset:39424
	ds_read_b128 v[230:233], v112 offset:32800
	ds_read_b128 v[234:237], v112 offset:39456
	ds_read_b128 v[238:241], v112 offset:32832
	ds_read_b128 v[242:245], v112 offset:39488
	ds_read_b128 v[246:249], v112 offset:32864
	ds_read_b128 v[250:253], v112 offset:39520
	v_xor_b32_e32 v32, 0x80000000, v167
	v_mov_b32_e32 v33, v32
	v_mov_b32_e32 v34, v32
	v_mov_b32_e32 v35, v32
	v_mov_b32_e32 v36, v32
	v_mov_b32_e32 v37, v32
	v_mov_b32_e32 v38, v32
	v_mov_b32_e32 v39, v32
	v_mov_b32_e32 v40, v32
	v_mov_b32_e32 v41, v32
	v_mov_b32_e32 v42, v32
	v_mov_b32_e32 v43, v32
	v_mov_b32_e32 v44, v32
	v_mov_b32_e32 v45, v32
	v_mov_b32_e32 v46, v32
	v_mov_b32_e32 v47, v32
	s_mov_b32 s4, 0x4138aa3b
	s_waitcnt lgkmcnt(7)
	v_mfma_f32_32x32x16_bf16 v[48:63], v[222:225], v[100:103], v[32:47]
	s_waitcnt lgkmcnt(6)
	v_mfma_f32_32x32x16_bf16 v[32:47], v[226:229], v[100:103], v[32:47]
	ds_read_b128 v[222:225], v112 offset:32896
	ds_read_b128 v[226:229], v112 offset:32928
	s_waitcnt lgkmcnt(7)
	v_mfma_f32_32x32x16_bf16 v[48:63], v[230:233], v[96:99], v[48:63]
	s_waitcnt lgkmcnt(6)
	v_mfma_f32_32x32x16_bf16 v[32:47], v[234:237], v[96:99], v[32:47]
	ds_read_b128 v[230:233], v112 offset:39552
	ds_read_b128 v[234:237], v112 offset:39584
	s_waitcnt lgkmcnt(7)
	v_mfma_f32_32x32x16_bf16 v[48:63], v[238:241], v[92:95], v[48:63]
	s_waitcnt lgkmcnt(6)
	v_mfma_f32_32x32x16_bf16 v[32:47], v[242:245], v[92:95], v[32:47]
	s_waitcnt lgkmcnt(5)
	v_mfma_f32_32x32x16_bf16 v[48:63], v[246:249], v[88:91], v[48:63]
	s_waitcnt lgkmcnt(4)
	v_mfma_f32_32x32x16_bf16 v[32:47], v[250:253], v[88:91], v[32:47]
	s_waitcnt lgkmcnt(3)
	v_mfma_f32_32x32x16_bf16 v[48:63], v[222:225], v[84:87], v[48:63]
	s_waitcnt lgkmcnt(2)
	v_mfma_f32_32x32x16_bf16 v[48:63], v[226:229], v[80:83], v[48:63]
	s_waitcnt lgkmcnt(1)
	v_mfma_f32_32x32x16_bf16 v[32:47], v[230:233], v[84:87], v[32:47]
	s_nop 7
	v_max_f32_e32 v112, v48, v49
	v_max3_f32 v112, v112, v50, v51
	v_max3_f32 v112, v112, v52, v53
	v_max3_f32 v112, v112, v54, v55
	v_max3_f32 v112, v112, v56, v57
	s_waitcnt lgkmcnt(0)
	v_mfma_f32_32x32x16_bf16 v[32:47], v[234:237], v[80:83], v[32:47]
	v_max3_f32 v112, v112, v58, v59
	v_max3_f32 v112, v112, v60, v61
	v_max3_f32 v112, v112, v62, v63
	s_nop 8
	v_max3_f32 v112, v112, v32, v33
	v_max3_f32 v112, v112, v34, v35
	v_max3_f32 v112, v112, v36, v37
	v_max3_f32 v112, v112, v38, v39
	v_max3_f32 v112, v112, v40, v41
	v_max3_f32 v112, v112, v42, v43
	v_max3_f32 v112, v112, v44, v45
	v_max3_f32 v112, v112, v46, v47
	v_mov_b32_e32 v114, v112
	s_nop 1
	v_permlane32_swap_b32_e32 v112, v114
	v_max_f32_e32 v114, v112, v114
	v_cmp_ge_f32_e32 vcc, s4, v114
	s_cmp_eq_u64 vcc, exec
	v_mov_b32_e32 v112, 1.0
	s_cbranch_scc0 .LBB0_758

; DEVI void partialSM(f32x16& p0, f32x16& p1, float& m_reg, float& mn, float& alpha) {
;   constexpr float THR2 = THR * 1.4426950408889634f;
;   float pmax = p0[0];
; #pragma unroll
;   for (int r = 1; r < 16; ++r) pmax = fmaxf(pmax, p0[r]);
; #pragma unroll
;   for (int r = 0; r < 16; ++r) pmax = fmaxf(pmax, p1[r]);
;   { auto rr = __builtin_amdgcn_permlane32_swap(__float_as_uint(pmax), __float_as_uint(pmax), false, false);
;     pmax = fmaxf(__uint_as_float(rr[0]), __uint_as_float(rr[1])); }
;   mn = m_reg;
;   if (__builtin_expect(__all(pmax <= THR2), 1)) { alpha = 1.f; }
;   else {
;     const float d = fmaxf(pmax, 0.f);
;     alpha = __builtin_amdgcn_exp2f(-d); m_reg += d;
; #pragma unroll
;     for (int r = 0; r < 16; ++r) p0[r] -= d;
; #pragma unroll
;     for (int r = 0; r < 16; ++r) p1[r] -= d;
;   }
; #pragma unroll
;   for (int r = 0; r < 16; ++r) p0[r] = __builtin_amdgcn_exp2f(p0[r]);
; }
; DEVI void finishSM(f32x16& p0, f32x16& p1, float alpha, float& l_reg, bf16x8& pa0, bf16x8& pa1, bf16x8& pa2, bf16x8& pa3) {
; #pragma unroll
;   for (int r = 0; r < 16; ++r) p1[r] = __builtin_amdgcn_exp2f(p1[r]);
;   float ps = 0;
; #pragma unroll
;   for (int r = 0; r < 16; ++r) ps += p0[r];
; #pragma unroll
;   for (int r = 0; r < 16; ++r) ps += p1[r];
;   { auto rr = __builtin_amdgcn_permlane32_swap(__float_as_uint(ps), __float_as_uint(ps), false, false);
;     ps = __uint_as_float(rr[0]) + __uint_as_float(rr[1]); }
;   l_reg = l_reg * alpha + ps;
;     ...
;   PK4(p0, 0, pa0); PK4(p0, 8, pa1); PK4(p1, 0, pa2); PK4(p1, 8, pa3);
;     ...
; }
; DEVI void qkt(f32x16& p0, f32x16& p1, const char* Ks, const bf16x8* qr, int r32, int hi, float minit) {
; #pragma unroll
;   for (int r = 0; r < 16; ++r) { p0[r] = minit; p1[r] = minit; }
; #pragma unroll
;   for (int d0 = 0; d0 < 6; ++d0) {
;     int cb = d0 * 32 + hi * 16;
;     bf16x8 b0 = *reinterpret_cast<const bf16x8*>(Ks + r32 * KROW + cb);
;     bf16x8 b1 = *reinterpret_cast<const bf16x8*>(Ks + (32 + r32) * KROW + cb);
;     p0 = __builtin_amdgcn_mfma_f32_32x32x16_bf16(b0, qr[d0], p0, 0, 0, 0);
;     p1 = __builtin_amdgcn_mfma_f32_32x32x16_bf16(b1, qr[d0], p1, 0, 0, 0);
;   }
; }
; DEVI void attn_unit(const u16* __restrict__ Qb, const u16* __restrict__ Kh, const u16* __restrict__ Vh, u16* __restrict__ Yrow0, int seq, char* lds) {
;     ...
;       SBAR(); qkt(pA0, pA1, Kj1, qr, r32, hi, -m_reg);
.LBB0_746:
	s_andn2_saveexec_b64 s[6:7], s[6:7]
	s_cbranch_execz .LBB0_751
	v_add3_u32 v112, s30, v166, v128
	ds_read_b128 v[222:225], v112 offset:32768
	ds_read_b128 v[226:229], v112 offset:39424
	ds_read_b128 v[230:233], v112 offset:32800
	ds_read_b128 v[234:237], v112 offset:39456
	ds_read_b128 v[238:241], v112 offset:32832
	ds_read_b128 v[242:245], v112 offset:39488
	ds_read_b128 v[246:249], v112 offset:32864
	ds_read_b128 v[250:253], v112 offset:39520
	v_xor_b32_e32 v32, 0x80000000, v167
	v_mov_b32_e32 v33, v32
	v_mov_b32_e32 v34, v32
	v_mov_b32_e32 v35, v32
	v_mov_b32_e32 v36, v32
	v_mov_b32_e32 v37, v32
	v_mov_b32_e32 v38, v32
	v_mov_b32_e32 v39, v32
	v_mov_b32_e32 v40, v32
	v_mov_b32_e32 v41, v32
	v_mov_b32_e32 v42, v32
	v_mov_b32_e32 v43, v32
	v_mov_b32_e32 v44, v32
	v_mov_b32_e32 v45, v32
	v_mov_b32_e32 v46, v32
	v_mov_b32_e32 v47, v32
	s_waitcnt lgkmcnt(7)
	s_nop 0
	v_mfma_f32_32x32x16_bf16 v[48:63], v[222:225], v[100:103], v[32:47]
	s_waitcnt lgkmcnt(6)
	v_mfma_f32_32x32x16_bf16 v[32:47], v[226:229], v[100:103], v[32:47]
	ds_read_b128 v[222:225], v112 offset:32896
	ds_read_b128 v[226:229], v112 offset:39552
	s_waitcnt lgkmcnt(7)
	v_mfma_f32_32x32x16_bf16 v[48:63], v[230:233], v[96:99], v[48:63]
	s_waitcnt lgkmcnt(6)
	v_mfma_f32_32x32x16_bf16 v[32:47], v[234:237], v[96:99], v[32:47]
	ds_read_b128 v[230:233], v112 offset:32928
	ds_read_b128 v[234:237], v112 offset:39584
	s_waitcnt lgkmcnt(7)
	v_mfma_f32_32x32x16_bf16 v[48:63], v[238:241], v[92:95], v[48:63]
	s_waitcnt lgkmcnt(6)
	v_mfma_f32_32x32x16_bf16 v[32:47], v[242:245], v[92:95], v[32:47]
	s_waitcnt lgkmcnt(5)
	v_mfma_f32_32x32x16_bf16 v[48:63], v[246:249], v[88:91], v[48:63]
	s_waitcnt lgkmcnt(4)
	v_mfma_f32_32x32x16_bf16 v[32:47], v[250:253], v[88:91], v[32:47]
	s_waitcnt lgkmcnt(3)
	v_mfma_f32_32x32x16_bf16 v[48:63], v[222:225], v[84:87], v[48:63]
	s_waitcnt lgkmcnt(2)
	v_mfma_f32_32x32x16_bf16 v[32:47], v[226:229], v[84:87], v[32:47]
	v_add_f32_e32 v112, v185, v190
	v_add_f32_e32 v112, v188, v112
	v_add_f32_e32 v112, v114, v112
	v_add_f32_e32 v112, v186, v112
	v_add_f32_e32 v112, v115, v112
	v_add_f32_e32 v112, v184, v112
	v_add_f32_e32 v112, v116, v112
	v_add_f32_e32 v112, v183, v112
	v_add_f32_e32 v112, v117, v112
	v_add_f32_e32 v112, v182, v112
	v_add_f32_e32 v112, v118, v112
	v_add_f32_e32 v112, v181, v112
	v_add_f32_e32 v112, v119, v112
	v_add_f32_e32 v112, v180, v112
	v_add_f32_e32 v112, v112, v120
	v_add_f32_e32 v112, v121, v112
	v_add_f32_e32 v112, v122, v112
	v_add_f32_e32 v112, v123, v112
	v_add_f32_e32 v112, v176, v112
	v_add_f32_e32 v112, v177, v112
	v_add_f32_e32 v112, v178, v112
	v_add_f32_e32 v112, v179, v112
	v_add_f32_e32 v112, v124, v112
	v_add_f32_e32 v112, v125, v112
	s_waitcnt lgkmcnt(1)
	v_mfma_f32_32x32x16_bf16 v[48:63], v[230:233], v[80:83], v[48:63]
	v_add_f32_e32 v112, v126, v112
	v_add_f32_e32 v112, v127, v112
	v_add_f32_e32 v112, v172, v112
	v_add_f32_e32 v112, v173, v112
	v_add_f32_e32 v112, v174, v112
	v_add_f32_e32 v190, v175, v112
	v_mov_b32_e32 v191, v190
	s_waitcnt lgkmcnt(0)
	v_mfma_f32_32x32x16_bf16 v[32:47], v[234:237], v[80:83], v[32:47]
	v_cvt_pk_bf16_f32 v112, v187, v189
	v_cvt_pk_bf16_f32 v113, v185, v188
	v_cvt_pk_bf16_f32 v114, v114, v186
	v_cvt_pk_bf16_f32 v115, v115, v184
	v_cvt_pk_bf16_f32 v116, v116, v183
	v_cvt_pk_bf16_f32 v117, v117, v182
	v_cvt_pk_bf16_f32 v118, v118, v181
	v_cvt_pk_bf16_f32 v119, v119, v180
	v_cvt_pk_bf16_f32 v120, v120, v121
	v_cvt_pk_bf16_f32 v121, v122, v123
	v_cvt_pk_bf16_f32 v122, v176, v177
	v_cvt_pk_bf16_f32 v123, v178, v179
	v_cvt_pk_bf16_f32 v124, v124, v125
	v_cvt_pk_bf16_f32 v125, v126, v127
	v_cvt_pk_bf16_f32 v126, v172, v173
	v_cvt_pk_bf16_f32 v127, v174, v175
	v_permlane32_swap_b32_e32 v190, v191
	v_permlane32_swap_b32_e32 v112, v114
	v_permlane32_swap_b32_e32 v113, v115
	v_permlane32_swap_b32_e32 v116, v118
	v_permlane32_swap_b32_e32 v117, v119
	v_permlane32_swap_b32_e32 v120, v122
	v_permlane32_swap_b32_e32 v121, v123
	v_permlane32_swap_b32_e32 v124, v126
	v_permlane32_swap_b32_e32 v125, v127
	s_add_i32 s29, s9, 2
	s_cmp_ge_u32 s29, s8
	s_cbranch_scc1 .LBB0_749
	s_waitcnt vmcnt(0)
	global_load_dwordx4 v[64:67], v[202:203], off
	global_load_dwordx4 v[68:71], v[204:205], off
	global_load_dwordx4 v[72:75], v[206:207], off
.LBB0_749:
	ds_read_b64_tr_b16 v[172:173], v171 offset:0
	ds_read_b64_tr_b16 v[174:175], v171 offset:0x400
	ds_read_b64_tr_b16 v[176:177], v171 offset:0x800
	ds_read_b64_tr_b16 v[178:179], v171 offset:0xc00
	ds_read_b64_tr_b16 v[180:181], v171 offset:0x1000
	ds_read_b64_tr_b16 v[182:183], v171 offset:0x1400
	ds_read_b64_tr_b16 v[184:185], v171 offset:0x1800
	ds_read_b64_tr_b16 v[186:187], v171 offset:0x1c00
	s_waitcnt lgkmcnt(0)
	s_nop 0
	v_mfma_f32_32x32x16_bf16 v[0:15], v[112:115], v[172:175], v[0:15]
	ds_read_b64_tr_b16 v[172:173], v171 offset:0x200
	ds_read_b64_tr_b16 v[174:175], v171 offset:0x600
	v_mfma_f32_32x32x16_bf16 v[0:15], v[116:119], v[176:179], v[0:15]
	ds_read_b64_tr_b16 v[176:177], v171 offset:0xa00
	ds_read_b64_tr_b16 v[178:179], v171 offset:0xe00
	v_mfma_f32_32x32x16_bf16 v[0:15], v[120:123], v[180:183], v[0:15]
	ds_read_b64_tr_b16 v[180:181], v171 offset:0x1200
	ds_read_b64_tr_b16 v[182:183], v171 offset:0x1600
	v_mfma_f32_32x32x16_bf16 v[0:15], v[124:127], v[184:187], v[0:15]
	ds_read_b64_tr_b16 v[184:185], v171 offset:0x1a00
	ds_read_b64_tr_b16 v[186:187], v171 offset:0x1e00
	s_waitcnt lgkmcnt(0)
	v_mfma_f32_32x32x16_bf16 v[16:31], v[112:115], v[172:175], v[16:31]
	v_max_f32_e32 v112, v48, v49
	v_max3_f32 v112, v112, v50, v51
	v_max3_f32 v112, v112, v52, v53
	v_max3_f32 v112, v112, v54, v55
	v_max3_f32 v112, v112, v56, v57
	v_mfma_f32_32x32x16_bf16 v[16:31], v[116:119], v[176:179], v[16:31]
	v_max3_f32 v112, v112, v58, v59
	v_max3_f32 v112, v112, v60, v61
	v_max3_f32 v112, v112, v62, v63
	v_max3_f32 v112, v112, v32, v33
	v_max3_f32 v112, v112, v34, v35
	v_max3_f32 v112, v112, v36, v37
	v_max3_f32 v112, v112, v38, v39
	v_mfma_f32_32x32x16_bf16 v[16:31], v[120:123], v[180:183], v[16:31]
	v_max3_f32 v112, v112, v40, v41
	v_max3_f32 v112, v112, v42, v43
	v_max3_f32 v112, v112, v44, v45
	v_max3_f32 v112, v112, v46, v47
	v_mov_b32_e32 v113, v112
	s_nop 1
	v_permlane32_swap_b32_e32 v112, v113
	v_mfma_f32_32x32x16_bf16 v[16:31], v[124:127], v[184:187], v[16:31]
	v_max_f32_e32 v113, v112, v113
	s_mov_b32 s4, 0x4138aa3b
	v_cmp_ge_f32_e32 vcc, s4, v113
	s_cmp_eq_u64 vcc, exec
	v_mov_b32_e32 v112, 1.0
	s_cbranch_scc0 .LBB0_759
